# LayerNorm 1-3: the two row sums per row as DPP row reductions + readlane broadcast instead of six ds_bpermute round trips each
# speedup vs baseline: 1.0069x; 1.0037x over previous
; __device__ __forceinline__ void ln_phase(int wv, h16* X, const float* g, const float* b, float* out32, int G, const float* part, float alpha, float beta) {
;     ...
; #pragma unroll
;         for (int e = 0; e < 32; ++e) s += v[e];
;         const float mean = wave_sum(s) * (1.f / DM); float s2 = 0.f;
; #pragma unroll
;         for (int e = 0; e < 32; ++e) { v[e] -= mean; s2 += v[e] * v[e]; }
;         const float rstd = 1.f / sqrtf(wave_sum(s2) * (1.f / DM) + LN_EPS);
.LBB0_420:
	s_or_b64 exec, exec, s[8:9]
	v_add_f32_e32 v18, 0, v62
	v_add_f32_e32 v18, v63, v18
	v_add_f32_e32 v18, v60, v18
	v_add_f32_e32 v18, v61, v18
	v_add_f32_e32 v18, v58, v18
	v_add_f32_e32 v18, v59, v18
	v_add_f32_e32 v18, v28, v18
	v_add_f32_e32 v18, v29, v18
	v_add_f32_e32 v18, v30, v18
	v_add_f32_e32 v18, v31, v18
	v_add_f32_e32 v18, v64, v18
	v_add_f32_e32 v18, v65, v18
	v_add_f32_e32 v18, v24, v18
	v_add_f32_e32 v18, v25, v18
	v_add_f32_e32 v18, v66, v18
	v_add_f32_e32 v18, v67, v18
	v_add_f32_e32 v18, v26, v18
	v_add_f32_e32 v18, v27, v18
	v_add_f32_e32 v18, v68, v18
	v_add_f32_e32 v18, v69, v18
	v_add_f32_e32 v18, v20, v18
	v_add_f32_e32 v18, v21, v18
	v_add_f32_e32 v18, v70, v18
	v_add_f32_e32 v18, v71, v18
	v_add_f32_e32 v18, v22, v18
	v_add_f32_e32 v18, v23, v18
	v_add_f32_e32 v18, v72, v18
	v_add_f32_e32 v18, v73, v18
	v_add_f32_e32 v18, v16, v18
	v_add_f32_e32 v18, v17, v18
	v_add_f32_e32 v18, v74, v18
	v_add_f32_e32 v18, v75, v18
	v_mov_b32_e32 v160, v18
	s_nop 1
	v_add_f32_dpp v160, v160, v160 row_shr:1 row_mask:0xf bank_mask:0xf
	s_nop 1
	v_add_f32_dpp v160, v160, v160 row_shr:2 row_mask:0xf bank_mask:0xf
	s_nop 1
	v_add_f32_dpp v160, v160, v160 row_shr:4 row_mask:0xf bank_mask:0xf
	s_nop 1
	v_add_f32_dpp v160, v160, v160 row_shr:8 row_mask:0xf bank_mask:0xf
	s_nop 1
	v_add_f32_dpp v160, v160, v160 row_bcast:15 row_mask:0xa bank_mask:0xf
	s_nop 1
	v_add_f32_dpp v160, v160, v160 row_bcast:31 row_mask:0xc bank_mask:0xf
	s_nop 0
	v_readlane_b32 s98, v160, 63
	s_nop 1
	v_mov_b32_e32 v161, s98
	global_load_dwordx4 v[86:89], v[46:47], off offset:16
	global_load_dwordx4 v[90:93], v[46:47], off
	s_and_b64 s[6:7], exec, s[6:7]
	v_lshl_add_u64 v[38:39], v[38:39], 0, s[34:35]
	s_or_b64 s[16:17], s[6:7], s[16:17]
	v_mov_b32_e32 v76, v85
	v_mov_b32_e32 v18, v161
	v_mul_f32_e32 v32, 0x3a000000, v18
	v_pk_add_f32 v[62:63], v[62:63], v[32:33] op_sel_hi:[1,0] neg_lo:[0,1] neg_hi:[0,1]
	v_pk_add_f32 v[60:61], v[60:61], v[32:33] op_sel_hi:[1,0] neg_lo:[0,1] neg_hi:[0,1]
	v_pk_mul_f32 v[124:125], v[62:63], v[62:63]
	v_pk_add_f32 v[94:95], v[30:31], v[32:33] op_sel_hi:[1,0] neg_lo:[0,1] neg_hi:[0,1]
	v_pk_add_f32 v[96:97], v[64:65], v[32:33] op_sel_hi:[1,0] neg_lo:[0,1] neg_hi:[0,1]
	v_pk_add_f32 v[98:99], v[24:25], v[32:33] op_sel_hi:[1,0] neg_lo:[0,1] neg_hi:[0,1]
	v_pk_add_f32 v[100:101], v[66:67], v[32:33] op_sel_hi:[1,0] neg_lo:[0,1] neg_hi:[0,1]
	v_pk_add_f32 v[102:103], v[26:27], v[32:33] op_sel_hi:[1,0] neg_lo:[0,1] neg_hi:[0,1]
	v_pk_add_f32 v[104:105], v[68:69], v[32:33] op_sel_hi:[1,0] neg_lo:[0,1] neg_hi:[0,1]
	v_pk_add_f32 v[106:107], v[20:21], v[32:33] op_sel_hi:[1,0] neg_lo:[0,1] neg_hi:[0,1]
	v_pk_add_f32 v[108:109], v[70:71], v[32:33] op_sel_hi:[1,0] neg_lo:[0,1] neg_hi:[0,1]
	v_pk_add_f32 v[64:65], v[22:23], v[32:33] op_sel_hi:[1,0] neg_lo:[0,1] neg_hi:[0,1]
	v_pk_add_f32 v[66:67], v[72:73], v[32:33] op_sel_hi:[1,0] neg_lo:[0,1] neg_hi:[0,1]
	v_pk_add_f32 v[68:69], v[16:17], v[32:33] op_sel_hi:[1,0] neg_lo:[0,1] neg_hi:[0,1]
	v_pk_add_f32 v[70:71], v[74:75], v[32:33] op_sel_hi:[1,0] neg_lo:[0,1] neg_hi:[0,1]
	v_pk_mul_f32 v[126:127], v[60:61], v[60:61]
	v_pk_add_f32 v[58:59], v[58:59], v[32:33] op_sel_hi:[1,0] neg_lo:[0,1] neg_hi:[0,1]
	v_pk_add_f32 v[28:29], v[28:29], v[32:33] op_sel_hi:[1,0] neg_lo:[0,1] neg_hi:[0,1]
	v_add_f32_e32 v32, v124, v125
	v_add_f32_e32 v32, v126, v32
	v_pk_mul_f32 v[128:129], v[58:59], v[58:59]
	v_add_f32_e32 v32, v127, v32
	v_add_f32_e32 v32, v128, v32
	v_pk_mul_f32 v[130:131], v[28:29], v[28:29]
	v_add_f32_e32 v32, v129, v32
	v_add_f32_e32 v32, v130, v32
	v_pk_mul_f32 v[24:25], v[94:95], v[94:95]
	v_add_f32_e32 v32, v131, v32
	v_add_f32_e32 v24, v24, v32
	v_pk_mul_f32 v[26:27], v[96:97], v[96:97]
	v_add_f32_e32 v24, v25, v24
	v_add_f32_e32 v24, v26, v24
	v_pk_mul_f32 v[30:31], v[98:99], v[98:99]
	v_add_f32_e32 v24, v27, v24
	v_add_f32_e32 v24, v30, v24
	v_pk_mul_f32 v[72:73], v[100:101], v[100:101]
	v_add_f32_e32 v24, v31, v24
	v_add_f32_e32 v24, v72, v24
	v_pk_mul_f32 v[74:75], v[102:103], v[102:103]
	v_add_f32_e32 v24, v73, v24
	v_add_f32_e32 v24, v74, v24
	v_pk_mul_f32 v[110:111], v[104:105], v[104:105]
	global_load_dwordx4 v[16:19], v[48:49], off offset:16
	global_load_dwordx4 v[20:23], v[48:49], off
	global_load_dwordx4 v[204:207], v[48:49], off offset:2048
	global_load_dwordx4 v[208:211], v[46:47], off offset:2048
	global_load_dwordx4 v[212:215], v[46:47], off offset:2064
	global_load_dwordx4 v[216:219], v[48:49], off offset:2064
	global_load_dwordx4 v[220:223], v[52:53], off
	global_load_dwordx4 v[224:227], v[50:51], off
	global_load_dwordx4 v[228:231], v[50:51], off offset:16
	global_load_dwordx4 v[232:235], v[52:53], off offset:16
	global_load_dwordx4 v[240:243], v[56:57], off
	global_load_dwordx4 v[244:247], v[54:55], off
	global_load_dwordx4 v[248:251], v[54:55], off offset:16
	global_load_dwordx4 v[252:255], v[56:57], off offset:16
	v_add_f32_e32 v24, v75, v24
	v_add_f32_e32 v24, v110, v24
	v_pk_mul_f32 v[112:113], v[106:107], v[106:107]
	v_add_f32_e32 v24, v111, v24
	v_add_f32_e32 v24, v112, v24
	v_pk_mul_f32 v[114:115], v[108:109], v[108:109]
	v_add_f32_e32 v24, v113, v24
	v_add_f32_e32 v24, v114, v24
; __device__ __forceinline__ void ln_phase(int wv, h16* X, const float* g, const float* b, float* out32, int G, const float* part, float alpha, float beta) {
;     ...
;         const float rstd = 1.f / sqrtf(wave_sum(s2) * (1.f / DM) + LN_EPS);
; #pragma unroll
;         for (int j = 0; j < 4; ++j) { const int c0 = j * 512 + lane * 8;
;             const f32x4 g0 = *(const f32x4*)(g + c0), g1 = *(const f32x4*)(g + c0 + 4), b0 = *(const f32x4*)(b + c0), b1 = *(const f32x4*)(b + c0 + 4);
;             f32x4 o0, o1;
; #pragma unroll
;             for (int e = 0; e < 4; ++e) { o0[e] = v[j * 8 + e] * rstd * g0[e] + b0[e]; o1[e] = v[j * 8 + 4 + e] * rstd * g1[e] + b1[e]; }
;             if (out32) { *(f32x4*)(out32 + (size_t)row * DM + c0) = o0; *(f32x4*)(out32 + (size_t)row * DM + c0 + 4) = o1; }
;             else *(u32x4*)(xr + c0) = pg8::pack8(o0, o1); }
	v_pk_mul_f32 v[116:117], v[64:65], v[64:65]
	v_add_f32_e32 v24, v115, v24
	v_add_f32_e32 v24, v116, v24
	v_pk_mul_f32 v[118:119], v[66:67], v[66:67]
	v_add_f32_e32 v24, v117, v24
	v_add_f32_e32 v24, v118, v24
	v_pk_mul_f32 v[120:121], v[68:69], v[68:69]
	v_add_f32_e32 v24, v119, v24
	v_add_f32_e32 v24, v120, v24
	v_pk_mul_f32 v[122:123], v[70:71], v[70:71]
	v_add_f32_e32 v24, v121, v24
	v_add_f32_e32 v24, v122, v24
	v_add_f32_e32 v24, v123, v24
	v_mov_b32_e32 v160, v24
	s_nop 1
	v_add_f32_dpp v160, v160, v160 row_shr:1 row_mask:0xf bank_mask:0xf
	s_nop 1
	v_add_f32_dpp v160, v160, v160 row_shr:2 row_mask:0xf bank_mask:0xf
	s_nop 1
	v_add_f32_dpp v160, v160, v160 row_shr:4 row_mask:0xf bank_mask:0xf
	s_nop 1
	v_add_f32_dpp v160, v160, v160 row_shr:8 row_mask:0xf bank_mask:0xf
	s_nop 1
	v_add_f32_dpp v160, v160, v160 row_bcast:15 row_mask:0xa bank_mask:0xf
	s_nop 1
	v_add_f32_dpp v160, v160, v160 row_bcast:31 row_mask:0xc bank_mask:0xf
	s_nop 0
	v_readlane_b32 s98, v160, 63
	s_nop 1
	v_mov_b32_e32 v161, s98
	v_mov_b32_e32 v24, v161
	v_fmamk_f32 v24, v24, 0x3a000000, v77
	v_mul_f32_e32 v25, 0x4f800000, v24
	v_cmp_gt_f32_e32 vcc, s37, v24
	s_nop 1
	v_cndmask_b32_e32 v24, v24, v25, vcc
	v_sqrt_f32_e32 v25, v24
	s_nop 0
	v_add_u32_e32 v26, -1, v25
	v_add_u32_e32 v27, 1, v25
	v_fma_f32 v30, -v26, v25, v24
	v_fma_f32 v31, -v27, v25, v24
	v_cmp_ge_f32_e64 s[8:9], 0, v30
	s_nop 1
	v_cndmask_b32_e64 v25, v25, v26, s[8:9]
	v_cmp_lt_f32_e64 s[8:9], 0, v31
	s_nop 1
	v_cndmask_b32_e64 v25, v25, v27, s[8:9]
	v_mul_f32_e32 v26, 0x37800000, v25
	v_cndmask_b32_e32 v25, v25, v26, vcc
	v_cmp_class_f32_e32 vcc, v24, v78
	s_nop 1
	v_cndmask_b32_e32 v26, v25, v24, vcc
	v_div_scale_f32 v27, s[8:9], v26, v26, 1.0
	v_rcp_f32_e32 v30, v27
	v_div_scale_f32 v31, vcc, 1.0, v26, 1.0
	v_lshl_add_u64 v[24:25], v[36:37], 0, v[34:35]
	v_fma_f32 v32, -v27, v30, 1.0
	v_fmac_f32_e32 v30, v32, v30
	v_mul_f32_e32 v32, v31, v30
	v_fma_f32 v72, -v27, v32, v31
	v_fmac_f32_e32 v32, v72, v30
	v_fma_f32 v27, -v27, v32, v31
	v_div_fmas_f32 v27, v27, v30, v32
	v_div_fixup_f32 v32, v27, v26, 1.0
	v_pk_mul_f32 v[26:27], v[62:63], v[32:33] op_sel_hi:[1,0]
	v_pk_mul_f32 v[30:31], v[58:59], v[32:33] op_sel_hi:[1,0]
	v_pk_mul_f32 v[58:59], v[60:61], v[32:33] op_sel_hi:[1,0]
	v_pk_mul_f32 v[28:29], v[28:29], v[32:33] op_sel_hi:[1,0]
	s_waitcnt vmcnt(0)
	v_pk_fma_f32 v[20:21], v[90:91], v[26:27], v[20:21]
	v_pk_fma_f32 v[26:27], v[86:87], v[30:31], v[16:17]
	v_pk_fma_f32 v[22:23], v[92:93], v[58:59], v[22:23]
	v_pk_fma_f32 v[28:29], v[88:89], v[28:29], v[18:19]
	v_add_co_u32_e32 v62, vcc, s3, v24
	v_cvt_pk_f16_f32 v16, v20, v21
	v_cvt_pk_f16_f32 v17, v22, v23
	v_cvt_pk_f16_f32 v18, v26, v27
	v_cvt_pk_f16_f32 v19, v28, v29
	v_addc_co_u32_e32 v63, vcc, 0, v25, vcc
	global_store_dwordx4 v[62:63], v[16:19], off
	s_nop 0
	v_pk_mul_f32 v[58:59], v[94:95], v[32:33] op_sel_hi:[1,0]
	v_pk_mul_f32 v[60:61], v[96:97], v[32:33] op_sel_hi:[1,0]
	v_pk_mul_f32 v[72:73], v[98:99], v[32:33] op_sel_hi:[1,0]
	v_pk_mul_f32 v[74:75], v[100:101], v[32:33] op_sel_hi:[1,0]
	v_pk_mul_f32 v[64:65], v[64:65], v[32:33] op_sel_hi:[1,0]
	v_pk_mul_f32 v[66:67], v[66:67], v[32:33] op_sel_hi:[1,0]
	v_pk_mul_f32 v[68:69], v[68:69], v[32:33] op_sel_hi:[1,0]
	v_pk_mul_f32 v[70:71], v[70:71], v[32:33] op_sel_hi:[1,0]
	v_lshl_add_u64 v[36:37], v[36:37], 0, s[34:35]
	v_pk_fma_f32 v[16:17], v[208:209], v[58:59], v[204:205]
	v_pk_fma_f32 v[18:19], v[210:211], v[60:61], v[206:207]
	v_pk_fma_f32 v[20:21], v[212:213], v[72:73], v[216:217]
	v_pk_fma_f32 v[22:23], v[214:215], v[74:75], v[218:219]
	v_cvt_pk_f16_f32 v16, v16, v17
	v_cvt_pk_f16_f32 v17, v18, v19
	v_cvt_pk_f16_f32 v18, v20, v21
	v_cvt_pk_f16_f32 v19, v22, v23
	global_store_dwordx4 v[62:63], v[16:19], off offset:1024
	s_nop 0
	v_pk_mul_f32 v[58:59], v[102:103], v[32:33] op_sel_hi:[1,0]
	v_pk_mul_f32 v[60:61], v[104:105], v[32:33] op_sel_hi:[1,0]
	v_pk_mul_f32 v[72:73], v[106:107], v[32:33] op_sel_hi:[1,0]
	v_pk_mul_f32 v[74:75], v[108:109], v[32:33] op_sel_hi:[1,0]
	v_pk_fma_f32 v[16:17], v[224:225], v[58:59], v[220:221]
	v_pk_fma_f32 v[18:19], v[226:227], v[60:61], v[222:223]
	v_pk_fma_f32 v[20:21], v[228:229], v[72:73], v[232:233]
	v_pk_fma_f32 v[22:23], v[230:231], v[74:75], v[234:235]
	v_cvt_pk_f16_f32 v16, v16, v17
	v_cvt_pk_f16_f32 v17, v18, v19
	v_cvt_pk_f16_f32 v18, v20, v21
	v_cvt_pk_f16_f32 v19, v22, v23
	global_store_dwordx4 v[62:63], v[16:19], off offset:2048
	v_mov_b64_e32 v[30:31], v[2:3]
	v_mov_b64_e32 v[26:27], v[6:7]
	v_mov_b64_e32 v[22:23], v[10:11]
	v_mov_b64_e32 v[18:19], v[14:15]
	v_mov_b64_e32 v[28:29], v[0:1]
	v_mov_b64_e32 v[24:25], v[4:5]
	v_mov_b64_e32 v[20:21], v[8:9]
	v_mov_b64_e32 v[16:17], v[12:13]
	v_pk_fma_f32 v[58:59], v[244:245], v[64:65], v[240:241]
	v_pk_fma_f32 v[60:61], v[246:247], v[66:67], v[242:243]
	v_pk_fma_f32 v[64:65], v[248:249], v[68:69], v[252:253]
	v_pk_fma_f32 v[66:67], v[250:251], v[70:71], v[254:255]
	v_cvt_pk_f16_f32 v58, v58, v59
	v_cvt_pk_f16_f32 v59, v60, v61
	v_cvt_pk_f16_f32 v60, v64, v65
	v_cvt_pk_f16_f32 v61, v66, v67
	global_store_dwordx4 v[62:63], v[58:61], off offset:3072
	s_andn2_b64 exec, exec, s[16:17]
	s_cbranch_execz .LBB0_425

; __device__ __forceinline__ void ln_phase(int wv, h16* X, const float* g, const float* b, float* out32, int G, const float* part, float alpha, float beta) {
;     ...
; #pragma unroll
;         for (int e = 0; e < 32; ++e) s += v[e];
;         const float mean = wave_sum(s) * (1.f / DM); float s2 = 0.f;
; #pragma unroll
;         for (int e = 0; e < 32; ++e) { v[e] -= mean; s2 += v[e] * v[e]; }
;         const float rstd = 1.f / sqrtf(wave_sum(s2) * (1.f / DM) + LN_EPS);
.LBB0_2266:
	s_or_b64 exec, exec, s[8:9]
	v_add_f32_e32 v18, 0, v66
	v_add_f32_e32 v18, v67, v18
	v_add_f32_e32 v18, v64, v18
	v_add_f32_e32 v18, v65, v18
	v_add_f32_e32 v18, v62, v18
	v_add_f32_e32 v18, v63, v18
	v_add_f32_e32 v18, v28, v18
	v_add_f32_e32 v18, v29, v18
	v_add_f32_e32 v18, v30, v18
	v_add_f32_e32 v18, v31, v18
	v_add_f32_e32 v18, v68, v18
	v_add_f32_e32 v18, v69, v18
	v_add_f32_e32 v18, v24, v18
	v_add_f32_e32 v18, v25, v18
	v_add_f32_e32 v18, v70, v18
	v_add_f32_e32 v18, v71, v18
	v_add_f32_e32 v18, v26, v18
	v_add_f32_e32 v18, v27, v18
	v_add_f32_e32 v18, v72, v18
	v_add_f32_e32 v18, v73, v18
	v_add_f32_e32 v18, v20, v18
	v_add_f32_e32 v18, v21, v18
	v_add_f32_e32 v18, v74, v18
	v_add_f32_e32 v18, v75, v18
	v_add_f32_e32 v18, v22, v18
	v_add_f32_e32 v18, v23, v18
	v_add_f32_e32 v18, v76, v18
	v_add_f32_e32 v18, v77, v18
	v_add_f32_e32 v18, v16, v18
	v_add_f32_e32 v18, v17, v18
	v_add_f32_e32 v18, v78, v18
	v_add_f32_e32 v18, v79, v18
	v_mov_b32_e32 v160, v18
	s_nop 1
	v_add_f32_dpp v160, v160, v160 row_shr:1 row_mask:0xf bank_mask:0xf
	s_nop 1
	v_add_f32_dpp v160, v160, v160 row_shr:2 row_mask:0xf bank_mask:0xf
	s_nop 1
	v_add_f32_dpp v160, v160, v160 row_shr:4 row_mask:0xf bank_mask:0xf
	s_nop 1
	v_add_f32_dpp v160, v160, v160 row_shr:8 row_mask:0xf bank_mask:0xf
	s_nop 1
	v_add_f32_dpp v160, v160, v160 row_bcast:15 row_mask:0xa bank_mask:0xf
	s_nop 1
	v_add_f32_dpp v160, v160, v160 row_bcast:31 row_mask:0xc bank_mask:0xf
	s_nop 0
	v_readlane_b32 s98, v160, 63
	s_nop 1
	v_mov_b32_e32 v161, s98
	global_load_dwordx4 v[84:87], v[52:53], off offset:16
	global_load_dwordx4 v[88:91], v[52:53], off
	s_and_b64 s[6:7], exec, s[6:7]
	v_lshl_add_u64 v[38:39], v[38:39], 0, s[10:11]
	s_or_b64 s[14:15], s[6:7], s[14:15]
	v_mov_b32_e32 v80, v83
	v_mov_b32_e32 v18, v161
	v_mul_f32_e32 v32, 0x3a000000, v18
	v_pk_add_f32 v[66:67], v[66:67], v[32:33] op_sel_hi:[1,0] neg_lo:[0,1] neg_hi:[0,1]
	v_pk_add_f32 v[64:65], v[64:65], v[32:33] op_sel_hi:[1,0] neg_lo:[0,1] neg_hi:[0,1]
	v_pk_mul_f32 v[122:123], v[66:67], v[66:67]
	v_pk_add_f32 v[92:93], v[30:31], v[32:33] op_sel_hi:[1,0] neg_lo:[0,1] neg_hi:[0,1]
	v_pk_add_f32 v[94:95], v[68:69], v[32:33] op_sel_hi:[1,0] neg_lo:[0,1] neg_hi:[0,1]
	v_pk_add_f32 v[96:97], v[24:25], v[32:33] op_sel_hi:[1,0] neg_lo:[0,1] neg_hi:[0,1]
	v_pk_add_f32 v[98:99], v[70:71], v[32:33] op_sel_hi:[1,0] neg_lo:[0,1] neg_hi:[0,1]
	v_pk_add_f32 v[100:101], v[26:27], v[32:33] op_sel_hi:[1,0] neg_lo:[0,1] neg_hi:[0,1]
	v_pk_add_f32 v[102:103], v[72:73], v[32:33] op_sel_hi:[1,0] neg_lo:[0,1] neg_hi:[0,1]
	v_pk_add_f32 v[104:105], v[20:21], v[32:33] op_sel_hi:[1,0] neg_lo:[0,1] neg_hi:[0,1]
	v_pk_add_f32 v[106:107], v[74:75], v[32:33] op_sel_hi:[1,0] neg_lo:[0,1] neg_hi:[0,1]
	v_pk_add_f32 v[68:69], v[22:23], v[32:33] op_sel_hi:[1,0] neg_lo:[0,1] neg_hi:[0,1]
	v_pk_add_f32 v[70:71], v[76:77], v[32:33] op_sel_hi:[1,0] neg_lo:[0,1] neg_hi:[0,1]
	v_pk_add_f32 v[72:73], v[16:17], v[32:33] op_sel_hi:[1,0] neg_lo:[0,1] neg_hi:[0,1]
	v_pk_add_f32 v[74:75], v[78:79], v[32:33] op_sel_hi:[1,0] neg_lo:[0,1] neg_hi:[0,1]
	v_pk_mul_f32 v[124:125], v[64:65], v[64:65]
	v_pk_add_f32 v[62:63], v[62:63], v[32:33] op_sel_hi:[1,0] neg_lo:[0,1] neg_hi:[0,1]
	v_pk_add_f32 v[28:29], v[28:29], v[32:33] op_sel_hi:[1,0] neg_lo:[0,1] neg_hi:[0,1]
	v_add_f32_e32 v32, v122, v123
	v_add_f32_e32 v32, v124, v32
	v_pk_mul_f32 v[126:127], v[62:63], v[62:63]
	v_add_f32_e32 v32, v125, v32
	v_add_f32_e32 v32, v126, v32
	v_pk_mul_f32 v[128:129], v[28:29], v[28:29]
	v_add_f32_e32 v32, v127, v32
	v_add_f32_e32 v32, v128, v32
	v_pk_mul_f32 v[24:25], v[92:93], v[92:93]
	v_add_f32_e32 v32, v129, v32
	v_add_f32_e32 v24, v24, v32
	v_pk_mul_f32 v[26:27], v[94:95], v[94:95]
	v_add_f32_e32 v24, v25, v24
	v_add_f32_e32 v24, v26, v24
	v_pk_mul_f32 v[30:31], v[96:97], v[96:97]
	v_add_f32_e32 v24, v27, v24
	v_add_f32_e32 v24, v30, v24
	v_pk_mul_f32 v[76:77], v[98:99], v[98:99]
	v_add_f32_e32 v24, v31, v24
	v_add_f32_e32 v24, v76, v24
	v_pk_mul_f32 v[78:79], v[100:101], v[100:101]
	v_add_f32_e32 v24, v77, v24
	v_add_f32_e32 v24, v78, v24
	v_pk_mul_f32 v[108:109], v[102:103], v[102:103]
	global_load_dwordx4 v[16:19], v[46:47], off offset:16
	global_load_dwordx4 v[20:23], v[46:47], off
	global_load_dwordx4 v[204:207], v[48:49], off
	global_load_dwordx4 v[208:211], v[54:55], off
	global_load_dwordx4 v[212:215], v[54:55], off offset:16
	global_load_dwordx4 v[216:219], v[48:49], off offset:16
	global_load_dwordx4 v[220:223], v[50:51], off
	global_load_dwordx4 v[224:227], v[56:57], off
	global_load_dwordx4 v[228:231], v[56:57], off offset:16
	global_load_dwordx4 v[232:235], v[50:51], off offset:16
	global_load_dwordx4 v[240:243], v[60:61], off
	global_load_dwordx4 v[244:247], v[58:59], off
	global_load_dwordx4 v[248:251], v[58:59], off offset:16
	global_load_dwordx4 v[252:255], v[60:61], off offset:16
	v_add_f32_e32 v24, v79, v24
	v_add_f32_e32 v24, v108, v24
	v_pk_mul_f32 v[110:111], v[104:105], v[104:105]
	v_add_f32_e32 v24, v109, v24
	v_add_f32_e32 v24, v110, v24
	v_pk_mul_f32 v[112:113], v[106:107], v[106:107]
	v_add_f32_e32 v24, v111, v24
	v_add_f32_e32 v24, v112, v24
; __device__ __forceinline__ void ln_phase(int wv, h16* X, const float* g, const float* b, float* out32, int G, const float* part, float alpha, float beta) {
;     ...
;         const float rstd = 1.f / sqrtf(wave_sum(s2) * (1.f / DM) + LN_EPS);
; #pragma unroll
;         for (int j = 0; j < 4; ++j) { const int c0 = j * 512 + lane * 8;
;             const f32x4 g0 = *(const f32x4*)(g + c0), g1 = *(const f32x4*)(g + c0 + 4), b0 = *(const f32x4*)(b + c0), b1 = *(const f32x4*)(b + c0 + 4);
;             f32x4 o0, o1;
; #pragma unroll
;             for (int e = 0; e < 4; ++e) { o0[e] = v[j * 8 + e] * rstd * g0[e] + b0[e]; o1[e] = v[j * 8 + 4 + e] * rstd * g1[e] + b1[e]; }
;             if (out32) { *(f32x4*)(out32 + (size_t)row * DM + c0) = o0; *(f32x4*)(out32 + (size_t)row * DM + c0 + 4) = o1; }
;             else *(u32x4*)(xr + c0) = pg8::pack8(o0, o1); }
	v_pk_mul_f32 v[114:115], v[68:69], v[68:69]
	v_add_f32_e32 v24, v113, v24
	v_add_f32_e32 v24, v114, v24
	v_pk_mul_f32 v[116:117], v[70:71], v[70:71]
	v_add_f32_e32 v24, v115, v24
	v_add_f32_e32 v24, v116, v24
	v_pk_mul_f32 v[118:119], v[72:73], v[72:73]
	v_add_f32_e32 v24, v117, v24
	v_add_f32_e32 v24, v118, v24
	v_pk_mul_f32 v[120:121], v[74:75], v[74:75]
	v_add_f32_e32 v24, v119, v24
	v_add_f32_e32 v24, v120, v24
	v_add_f32_e32 v24, v121, v24
	v_mov_b32_e32 v160, v24
	s_nop 1
	v_add_f32_dpp v160, v160, v160 row_shr:1 row_mask:0xf bank_mask:0xf
	s_nop 1
	v_add_f32_dpp v160, v160, v160 row_shr:2 row_mask:0xf bank_mask:0xf
	s_nop 1
	v_add_f32_dpp v160, v160, v160 row_shr:4 row_mask:0xf bank_mask:0xf
	s_nop 1
	v_add_f32_dpp v160, v160, v160 row_shr:8 row_mask:0xf bank_mask:0xf
	s_nop 1
	v_add_f32_dpp v160, v160, v160 row_bcast:15 row_mask:0xa bank_mask:0xf
	s_nop 1
	v_add_f32_dpp v160, v160, v160 row_bcast:31 row_mask:0xc bank_mask:0xf
	s_nop 0
	v_readlane_b32 s98, v160, 63
	s_nop 1
	v_mov_b32_e32 v161, s98
	v_mov_b32_e32 v24, v161
	v_fmamk_f32 v24, v24, 0x3a000000, v81
	v_mul_f32_e32 v25, 0x4f800000, v24
	v_cmp_gt_f32_e32 vcc, s31, v24
	s_nop 1
	v_cndmask_b32_e32 v24, v24, v25, vcc
	v_sqrt_f32_e32 v25, v24
	s_nop 0
	v_add_u32_e32 v26, -1, v25
	v_add_u32_e32 v27, 1, v25
	v_fma_f32 v30, -v26, v25, v24
	v_fma_f32 v31, -v27, v25, v24
	v_cmp_ge_f32_e64 s[8:9], 0, v30
	s_nop 1
	v_cndmask_b32_e64 v25, v25, v26, s[8:9]
	v_cmp_lt_f32_e64 s[8:9], 0, v31
	s_nop 1
	v_cndmask_b32_e64 v25, v25, v27, s[8:9]
	v_mul_f32_e32 v26, 0x37800000, v25
	v_cndmask_b32_e32 v25, v25, v26, vcc
	v_cmp_class_f32_e32 vcc, v24, v82
	s_nop 1
	v_cndmask_b32_e32 v26, v25, v24, vcc
	v_div_scale_f32 v27, s[8:9], v26, v26, 1.0
	v_rcp_f32_e32 v30, v27
	v_div_scale_f32 v31, vcc, 1.0, v26, 1.0
	v_lshl_add_u64 v[24:25], v[36:37], 0, v[34:35]
	v_fma_f32 v32, -v27, v30, 1.0
	v_fmac_f32_e32 v30, v32, v30
	v_mul_f32_e32 v32, v31, v30
	v_fma_f32 v76, -v27, v32, v31
	v_fmac_f32_e32 v32, v76, v30
	v_fma_f32 v27, -v27, v32, v31
	v_div_fmas_f32 v27, v27, v30, v32
	v_div_fixup_f32 v32, v27, v26, 1.0
	v_pk_mul_f32 v[26:27], v[66:67], v[32:33] op_sel_hi:[1,0]
	v_pk_mul_f32 v[30:31], v[62:63], v[32:33] op_sel_hi:[1,0]
	v_pk_mul_f32 v[62:63], v[64:65], v[32:33] op_sel_hi:[1,0]
	v_pk_mul_f32 v[28:29], v[28:29], v[32:33] op_sel_hi:[1,0]
	s_waitcnt vmcnt(0)
	v_pk_fma_f32 v[20:21], v[88:89], v[26:27], v[20:21]
	v_pk_fma_f32 v[26:27], v[84:85], v[30:31], v[16:17]
	v_pk_fma_f32 v[22:23], v[90:91], v[62:63], v[22:23]
	v_pk_fma_f32 v[28:29], v[86:87], v[28:29], v[18:19]
	v_add_co_u32_e32 v66, vcc, s3, v24
	v_cvt_pk_f16_f32 v16, v20, v21
	v_cvt_pk_f16_f32 v17, v22, v23
	v_cvt_pk_f16_f32 v18, v26, v27
	v_cvt_pk_f16_f32 v19, v28, v29
	v_addc_co_u32_e32 v67, vcc, 0, v25, vcc
	global_store_dwordx4 v[66:67], v[16:19], off
	s_nop 0
	v_pk_mul_f32 v[62:63], v[92:93], v[32:33] op_sel_hi:[1,0]
	v_pk_mul_f32 v[64:65], v[94:95], v[32:33] op_sel_hi:[1,0]
	v_pk_mul_f32 v[76:77], v[96:97], v[32:33] op_sel_hi:[1,0]
	v_pk_mul_f32 v[78:79], v[98:99], v[32:33] op_sel_hi:[1,0]
	v_pk_mul_f32 v[68:69], v[68:69], v[32:33] op_sel_hi:[1,0]
	v_pk_mul_f32 v[70:71], v[70:71], v[32:33] op_sel_hi:[1,0]
	v_pk_mul_f32 v[72:73], v[72:73], v[32:33] op_sel_hi:[1,0]
	v_pk_mul_f32 v[74:75], v[74:75], v[32:33] op_sel_hi:[1,0]
	v_lshl_add_u64 v[36:37], v[36:37], 0, s[10:11]
	v_pk_fma_f32 v[16:17], v[208:209], v[62:63], v[204:205]
	v_pk_fma_f32 v[18:19], v[210:211], v[64:65], v[206:207]
	v_pk_fma_f32 v[20:21], v[212:213], v[76:77], v[216:217]
	v_pk_fma_f32 v[22:23], v[214:215], v[78:79], v[218:219]
	v_cvt_pk_f16_f32 v16, v16, v17
	v_cvt_pk_f16_f32 v17, v18, v19
	v_cvt_pk_f16_f32 v18, v20, v21
	v_cvt_pk_f16_f32 v19, v22, v23
	global_store_dwordx4 v[66:67], v[16:19], off offset:1024
	s_nop 0
	v_pk_mul_f32 v[62:63], v[100:101], v[32:33] op_sel_hi:[1,0]
	v_pk_mul_f32 v[64:65], v[102:103], v[32:33] op_sel_hi:[1,0]
	v_pk_mul_f32 v[76:77], v[104:105], v[32:33] op_sel_hi:[1,0]
	v_pk_mul_f32 v[78:79], v[106:107], v[32:33] op_sel_hi:[1,0]
	v_pk_fma_f32 v[16:17], v[224:225], v[62:63], v[220:221]
	v_pk_fma_f32 v[18:19], v[226:227], v[64:65], v[222:223]
	v_pk_fma_f32 v[20:21], v[228:229], v[76:77], v[232:233]
	v_pk_fma_f32 v[22:23], v[230:231], v[78:79], v[234:235]
	v_cvt_pk_f16_f32 v16, v16, v17
	v_cvt_pk_f16_f32 v17, v18, v19
	v_cvt_pk_f16_f32 v18, v20, v21
	v_cvt_pk_f16_f32 v19, v22, v23
	global_store_dwordx4 v[66:67], v[16:19], off offset:2048
	v_mov_b64_e32 v[30:31], v[2:3]
	v_mov_b64_e32 v[26:27], v[6:7]
	v_mov_b64_e32 v[22:23], v[10:11]
	v_mov_b64_e32 v[18:19], v[14:15]
	v_mov_b64_e32 v[28:29], v[0:1]
	v_mov_b64_e32 v[24:25], v[4:5]
	v_mov_b64_e32 v[20:21], v[8:9]
	v_mov_b64_e32 v[16:17], v[12:13]
	v_pk_fma_f32 v[62:63], v[244:245], v[68:69], v[240:241]
	v_pk_fma_f32 v[64:65], v[246:247], v[70:71], v[242:243]
	v_pk_fma_f32 v[68:69], v[248:249], v[72:73], v[252:253]
	v_pk_fma_f32 v[70:71], v[250:251], v[74:75], v[254:255]
	v_cvt_pk_f16_f32 v62, v62, v63
	v_cvt_pk_f16_f32 v63, v64, v65
	v_cvt_pk_f16_f32 v64, v68, v69
	v_cvt_pk_f16_f32 v65, v70, v71
	global_store_dwordx4 v[66:67], v[62:65], off offset:3072
	s_andn2_b64 exec, exec, s[14:15]
	s_cbranch_execz .LBB0_2271

; __device__ __forceinline__ void ln_phase(int wv, h16* X, const float* g, const float* b, float* out32, int G, const float* part, float alpha, float beta) {
;     ...
;         for (int j = 0; j < 4; ++j) { const h16x8 h = __builtin_bit_cast(h16x8, cu[j]);
; #pragma unroll
;             for (int e = 0; e < 8; ++e) v[j * 8 + e] = (float)h[e]; }
;         if (part && row >= NP) {
; #pragma unroll
;             for (int j = 0; j < 4; ++j) { f32x4 a0 = {0.f, 0.f, 0.f, 0.f}, a1 = {0.f, 0.f, 0.f, 0.f};
; #pragma unroll
;                 for (int ks = 0; ks < 4; ++ks) { const float* p = part + ((size_t)ks * NS + (row - NP)) * DM + j * 512 + lane * 8; a0 += *(const f32x4*)p; a1 += *(const f32x4*)(p + 4); }
; #pragma unroll
;                 for (int e = 0; e < 4; ++e) { v[j * 8 + e] = alpha * v[j * 8 + e] + beta * a0[e]; v[j * 8 + 4 + e] = alpha * v[j * 8 + 4 + e] + beta * a1[e]; } } }
; #pragma unroll
;         for (int e = 0; e < 32; ++e) s += v[e];
;         const float mean = wave_sum(s) * (1.f / DM); float s2 = 0.f;
; #pragma unroll
;         for (int e = 0; e < 32; ++e) { v[e] -= mean; s2 += v[e] * v[e]; }
;         const float rstd = 1.f / sqrtf(wave_sum(s2) * (1.f / DM) + LN_EPS);
.LBB0_2528:
	s_or_b64 exec, exec, s[8:9]
	v_cvt_f32_f16_e32 v58, v28
	v_cvt_f32_f16_sdwa v59, v28 dst_sel:DWORD dst_unused:UNUSED_PAD src0_sel:WORD_1
	v_cvt_f32_f16_e32 v60, v29
	v_cvt_f32_f16_sdwa v61, v29 dst_sel:DWORD dst_unused:UNUSED_PAD src0_sel:WORD_1
	v_add_f32_e32 v28, 0, v58
	v_cvt_f32_f16_e32 v62, v30
	v_add_f32_e32 v28, v28, v59
	v_cvt_f32_f16_sdwa v63, v30 dst_sel:DWORD dst_unused:UNUSED_PAD src0_sel:WORD_1
	v_add_f32_e32 v28, v28, v60
	v_cvt_f32_f16_e32 v64, v31
	v_add_f32_e32 v28, v28, v61
	v_cvt_f32_f16_sdwa v65, v31 dst_sel:DWORD dst_unused:UNUSED_PAD src0_sel:WORD_1
	v_add_f32_e32 v28, v28, v62
	v_cvt_f32_f16_e32 v66, v24
	v_add_f32_e32 v28, v28, v63
	v_cvt_f32_f16_sdwa v67, v24 dst_sel:DWORD dst_unused:UNUSED_PAD src0_sel:WORD_1
	v_add_f32_e32 v28, v28, v64
	v_cvt_f32_f16_e32 v70, v25
	v_add_f32_e32 v28, v28, v65
	v_cvt_f32_f16_sdwa v71, v25 dst_sel:DWORD dst_unused:UNUSED_PAD src0_sel:WORD_1
	v_cvt_f32_f16_sdwa v69, v19 dst_sel:DWORD dst_unused:UNUSED_PAD src0_sel:WORD_1
	v_cvt_f32_f16_e32 v68, v19
	v_add_f32_e32 v19, v28, v66
	v_cvt_f32_f16_e32 v72, v26
	v_add_f32_e32 v19, v19, v67
	v_cvt_f32_f16_sdwa v73, v26 dst_sel:DWORD dst_unused:UNUSED_PAD src0_sel:WORD_1
	v_add_f32_e32 v19, v19, v70
	v_cvt_f32_f16_e32 v74, v27
	v_add_f32_e32 v19, v19, v71
	v_cvt_f32_f16_sdwa v75, v27 dst_sel:DWORD dst_unused:UNUSED_PAD src0_sel:WORD_1
	v_add_f32_e32 v19, v19, v72
	v_cvt_f32_f16_e32 v76, v20
	v_add_f32_e32 v19, v19, v73
	v_cvt_f32_f16_sdwa v77, v20 dst_sel:DWORD dst_unused:UNUSED_PAD src0_sel:WORD_1
	v_add_f32_e32 v19, v19, v74
	v_cvt_f32_f16_e32 v78, v21
	v_add_f32_e32 v19, v19, v75
	v_cvt_f32_f16_sdwa v79, v21 dst_sel:DWORD dst_unused:UNUSED_PAD src0_sel:WORD_1
	v_add_f32_e32 v19, v19, v76
	v_cvt_f32_f16_e32 v80, v22
	v_add_f32_e32 v19, v19, v77
	v_cvt_f32_f16_sdwa v81, v22 dst_sel:DWORD dst_unused:UNUSED_PAD src0_sel:WORD_1
	v_add_f32_e32 v19, v19, v78
	v_cvt_f32_f16_e32 v82, v23
	v_add_f32_e32 v19, v19, v79
	v_cvt_f32_f16_sdwa v83, v23 dst_sel:DWORD dst_unused:UNUSED_PAD src0_sel:WORD_1
	v_add_f32_e32 v19, v19, v80
	v_cvt_f32_f16_e32 v84, v16
	v_add_f32_e32 v19, v19, v81
	v_cvt_f32_f16_sdwa v85, v16 dst_sel:DWORD dst_unused:UNUSED_PAD src0_sel:WORD_1
	v_add_f32_e32 v16, v19, v82
	v_cvt_f32_f16_e32 v86, v17
	v_add_f32_e32 v16, v16, v83
	v_cvt_f32_f16_sdwa v87, v17 dst_sel:DWORD dst_unused:UNUSED_PAD src0_sel:WORD_1
	v_add_f32_e32 v16, v16, v84
	v_cvt_f32_f16_e32 v88, v18
	v_add_f32_e32 v16, v16, v85
	v_cvt_f32_f16_sdwa v89, v18 dst_sel:DWORD dst_unused:UNUSED_PAD src0_sel:WORD_1
	v_add_f32_e32 v16, v16, v86
	v_add_f32_e32 v16, v16, v87
	v_add_f32_e32 v16, v16, v88
	v_add_f32_e32 v16, v16, v89
	v_add_f32_e32 v16, v16, v68
	v_add_f32_e32 v16, v16, v69
	v_mov_b32_e32 v160, v16
	s_nop 1
	v_add_f32_dpp v160, v160, v160 row_shr:1 row_mask:0xf bank_mask:0xf
	s_nop 1
	v_add_f32_dpp v160, v160, v160 row_shr:2 row_mask:0xf bank_mask:0xf
	s_nop 1
	v_add_f32_dpp v160, v160, v160 row_shr:4 row_mask:0xf bank_mask:0xf
	s_nop 1
	v_add_f32_dpp v160, v160, v160 row_shr:8 row_mask:0xf bank_mask:0xf
	s_nop 1
	v_add_f32_dpp v160, v160, v160 row_bcast:15 row_mask:0xa bank_mask:0xf
	s_nop 1
	v_add_f32_dpp v160, v160, v160 row_bcast:31 row_mask:0xc bank_mask:0xf
	s_nop 0
	v_readlane_b32 s98, v160, 63
	s_nop 1
	v_mov_b32_e32 v161, s98
	s_and_b64 s[6:7], exec, s[6:7]
	v_lshl_add_u64 v[38:39], v[38:39], 0, s[10:11]
	s_or_b64 s[14:15], s[6:7], s[14:15]
	global_load_dwordx4 v[16:19], v[46:47], off offset:16
	global_load_dwordx4 v[20:23], v[46:47], off
	global_load_dwordx4 v[24:27], v[40:41], off offset:16
	global_load_dwordx4 v[28:31], v[40:41], off
	global_load_dwordx4 v[204:207], v[48:49], off offset:16
	global_load_dwordx4 v[208:211], v[48:49], off
	global_load_dwordx4 v[212:215], v[42:43], off
	global_load_dwordx4 v[216:219], v[42:43], off offset:16
	global_load_dwordx4 v[220:223], v[50:51], off offset:16
	global_load_dwordx4 v[224:227], v[50:51], off
	global_load_dwordx4 v[228:231], v[44:45], off
	global_load_dwordx4 v[232:235], v[44:45], off offset:16
	global_load_dwordx4 v[240:243], v[52:53], off offset:16
	global_load_dwordx4 v[244:247], v[52:53], off
	global_load_dwordx4 v[248:251], v[54:55], off
	global_load_dwordx4 v[252:255], v[54:55], off offset:16
	v_mov_b32_e32 v57, v161
	v_mul_f32_e32 v90, 0x3a000000, v57
	v_pk_add_f32 v[58:59], v[58:59], v[90:91] op_sel_hi:[1,0] neg_lo:[0,1] neg_hi:[0,1]
	v_pk_add_f32 v[60:61], v[60:61], v[90:91] op_sel_hi:[1,0] neg_lo:[0,1] neg_hi:[0,1]
	v_pk_mul_f32 v[92:93], v[58:59], v[58:59]
	v_pk_mul_f32 v[94:95], v[60:61], v[60:61]
	v_add_f32_e32 v57, v92, v93
	v_pk_add_f32 v[62:63], v[62:63], v[90:91] op_sel_hi:[1,0] neg_lo:[0,1] neg_hi:[0,1]
	v_add_f32_e32 v57, v94, v57
	v_pk_mul_f32 v[96:97], v[62:63], v[62:63]
	v_add_f32_e32 v57, v95, v57
	v_pk_add_f32 v[64:65], v[64:65], v[90:91] op_sel_hi:[1,0] neg_lo:[0,1] neg_hi:[0,1]
	v_add_f32_e32 v57, v96, v57
	v_pk_mul_f32 v[98:99], v[64:65], v[64:65]
	v_add_f32_e32 v57, v97, v57
	v_pk_add_f32 v[66:67], v[66:67], v[90:91] op_sel_hi:[1,0] neg_lo:[0,1] neg_hi:[0,1]
	v_add_f32_e32 v57, v98, v57
	v_pk_mul_f32 v[100:101], v[66:67], v[66:67]
	v_add_f32_e32 v57, v99, v57
	v_pk_add_f32 v[70:71], v[70:71], v[90:91] op_sel_hi:[1,0] neg_lo:[0,1] neg_hi:[0,1]
	v_add_f32_e32 v57, v100, v57
	v_pk_mul_f32 v[102:103], v[70:71], v[70:71]
	v_add_f32_e32 v57, v101, v57
	v_pk_add_f32 v[72:73], v[72:73], v[90:91] op_sel_hi:[1,0] neg_lo:[0,1] neg_hi:[0,1]
	v_add_f32_e32 v57, v102, v57
	v_pk_mul_f32 v[104:105], v[72:73], v[72:73]
	v_add_f32_e32 v57, v103, v57
	v_pk_add_f32 v[74:75], v[74:75], v[90:91] op_sel_hi:[1,0] neg_lo:[0,1] neg_hi:[0,1]
	v_add_f32_e32 v57, v104, v57
; __device__ __forceinline__ void ln_phase(int wv, h16* X, const float* g, const float* b, float* out32, int G, const float* part, float alpha, float beta) {
;     ...
;         for (int e = 0; e < 32; ++e) { v[e] -= mean; s2 += v[e] * v[e]; }
;         const float rstd = 1.f / sqrtf(wave_sum(s2) * (1.f / DM) + LN_EPS);
; #pragma unroll
;         for (int j = 0; j < 4; ++j) { const int c0 = j * 512 + lane * 8;
;             const f32x4 g0 = *(const f32x4*)(g + c0), g1 = *(const f32x4*)(g + c0 + 4), b0 = *(const f32x4*)(b + c0), b1 = *(const f32x4*)(b + c0 + 4);
;             f32x4 o0, o1;
; #pragma unroll
;             for (int e = 0; e < 4; ++e) { o0[e] = v[j * 8 + e] * rstd * g0[e] + b0[e]; o1[e] = v[j * 8 + 4 + e] * rstd * g1[e] + b1[e]; }
;             if (out32) { *(f32x4*)(out32 + (size_t)row * DM + c0) = o0; *(f32x4*)(out32 + (size_t)row * DM + c0 + 4) = o1; }
;             else *(u32x4*)(xr + c0) = pg8::pack8(o0, o1); }
	v_pk_mul_f32 v[106:107], v[74:75], v[74:75]
	v_add_f32_e32 v57, v105, v57
	v_pk_add_f32 v[76:77], v[76:77], v[90:91] op_sel_hi:[1,0] neg_lo:[0,1] neg_hi:[0,1]
	v_add_f32_e32 v57, v106, v57
	v_pk_mul_f32 v[108:109], v[76:77], v[76:77]
	v_add_f32_e32 v57, v107, v57
	v_pk_add_f32 v[78:79], v[78:79], v[90:91] op_sel_hi:[1,0] neg_lo:[0,1] neg_hi:[0,1]
	v_add_f32_e32 v57, v108, v57
	v_pk_mul_f32 v[110:111], v[78:79], v[78:79]
	v_add_f32_e32 v57, v109, v57
	v_pk_add_f32 v[80:81], v[80:81], v[90:91] op_sel_hi:[1,0] neg_lo:[0,1] neg_hi:[0,1]
	v_add_f32_e32 v57, v110, v57
	v_pk_mul_f32 v[112:113], v[80:81], v[80:81]
	v_add_f32_e32 v57, v111, v57
	v_pk_add_f32 v[82:83], v[82:83], v[90:91] op_sel_hi:[1,0] neg_lo:[0,1] neg_hi:[0,1]
	v_add_f32_e32 v57, v112, v57
	v_pk_mul_f32 v[114:115], v[82:83], v[82:83]
	v_add_f32_e32 v57, v113, v57
	v_pk_add_f32 v[84:85], v[84:85], v[90:91] op_sel_hi:[1,0] neg_lo:[0,1] neg_hi:[0,1]
	v_add_f32_e32 v57, v114, v57
	v_pk_mul_f32 v[116:117], v[84:85], v[84:85]
	v_add_f32_e32 v57, v115, v57
	v_pk_add_f32 v[86:87], v[86:87], v[90:91] op_sel_hi:[1,0] neg_lo:[0,1] neg_hi:[0,1]
	v_add_f32_e32 v57, v116, v57
	v_pk_mul_f32 v[118:119], v[86:87], v[86:87]
	v_add_f32_e32 v57, v117, v57
	v_pk_add_f32 v[88:89], v[88:89], v[90:91] op_sel_hi:[1,0] neg_lo:[0,1] neg_hi:[0,1]
	v_add_f32_e32 v57, v118, v57
	v_pk_mul_f32 v[120:121], v[88:89], v[88:89]
	v_add_f32_e32 v57, v119, v57
	v_pk_add_f32 v[90:91], v[68:69], v[90:91] op_sel_hi:[1,0] neg_lo:[0,1] neg_hi:[0,1]
	v_add_f32_e32 v57, v120, v57
	v_pk_mul_f32 v[68:69], v[90:91], v[90:91]
	v_add_f32_e32 v57, v121, v57
	v_add_f32_e32 v57, v68, v57
	v_add_f32_e32 v57, v69, v57
	v_mov_b32_e32 v160, v57
	s_nop 1
	v_add_f32_dpp v160, v160, v160 row_shr:1 row_mask:0xf bank_mask:0xf
	s_nop 1
	v_add_f32_dpp v160, v160, v160 row_shr:2 row_mask:0xf bank_mask:0xf
	s_nop 1
	v_add_f32_dpp v160, v160, v160 row_shr:4 row_mask:0xf bank_mask:0xf
	s_nop 1
	v_add_f32_dpp v160, v160, v160 row_shr:8 row_mask:0xf bank_mask:0xf
	s_nop 1
	v_add_f32_dpp v160, v160, v160 row_bcast:15 row_mask:0xa bank_mask:0xf
	s_nop 1
	v_add_f32_dpp v160, v160, v160 row_bcast:31 row_mask:0xc bank_mask:0xf
	s_nop 0
	v_readlane_b32 s98, v160, 63
	s_nop 1
	v_mov_b32_e32 v161, s98
	v_mov_b32_e32 v57, v161
	v_fmamk_f32 v57, v57, 0x3a000000, v33
	v_mul_f32_e32 v68, 0x4f800000, v57
	v_cmp_gt_f32_e32 vcc, s4, v57
	s_nop 1
	v_cndmask_b32_e32 v57, v57, v68, vcc
	v_sqrt_f32_e32 v68, v57
	s_nop 0
	v_add_u32_e32 v69, -1, v68
	v_fma_f32 v92, -v69, v68, v57
	v_cmp_ge_f32_e64 s[8:9], 0, v92
	v_add_u32_e32 v92, 1, v68
	s_nop 0
	v_cndmask_b32_e64 v69, v68, v69, s[8:9]
	v_fma_f32 v68, -v92, v68, v57
	v_cmp_lt_f32_e64 s[8:9], 0, v68
	s_nop 1
	v_cndmask_b32_e64 v68, v69, v92, s[8:9]
	v_mul_f32_e32 v69, 0x37800000, v68
	v_cndmask_b32_e32 v68, v68, v69, vcc
	v_cmp_class_f32_e32 vcc, v57, v56
	s_nop 1
	v_cndmask_b32_e32 v57, v68, v57, vcc
	v_div_scale_f32 v92, s[8:9], v57, v57, 1.0
	v_rcp_f32_e32 v93, v92
	v_lshl_add_u64 v[68:69], v[36:37], 0, v[34:35]
	v_lshl_add_u64 v[36:37], v[36:37], 0, s[10:11]
	v_fma_f32 v94, -v92, v93, 1.0
	v_fmac_f32_e32 v93, v94, v93
	v_div_scale_f32 v94, vcc, 1.0, v57, 1.0
	v_mul_f32_e32 v95, v94, v93
	v_fma_f32 v96, -v92, v95, v94
	v_fmac_f32_e32 v95, v96, v93
	v_fma_f32 v92, -v92, v95, v94
	v_div_fmas_f32 v92, v92, v93, v95
	v_div_fixup_f32 v92, v92, v57, 1.0
	v_pk_mul_f32 v[58:59], v[58:59], v[92:93] op_sel_hi:[1,0]
	v_add_co_u32_e32 v94, vcc, s3, v68
	s_waitcnt vmcnt(0)
	v_pk_fma_f32 v[20:21], v[20:21], v[58:59], v[28:29]
	v_pk_mul_f32 v[28:29], v[62:63], v[92:93] op_sel_hi:[1,0]
	v_addc_co_u32_e32 v95, vcc, 0, v69, vcc
	v_pk_fma_f32 v[24:25], v[16:17], v[28:29], v[24:25]
	v_pk_mul_f32 v[16:17], v[60:61], v[92:93] op_sel_hi:[1,0]
	v_pk_mul_f32 v[58:59], v[66:67], v[92:93] op_sel_hi:[1,0]
	v_pk_fma_f32 v[22:23], v[22:23], v[16:17], v[30:31]
	v_pk_mul_f32 v[16:17], v[64:65], v[92:93] op_sel_hi:[1,0]
	v_pk_mul_f32 v[60:61], v[72:73], v[92:93] op_sel_hi:[1,0]
	v_pk_fma_f32 v[26:27], v[18:19], v[16:17], v[26:27]
	v_cvt_pk_f16_f32 v16, v20, v21
	v_cvt_pk_f16_f32 v17, v22, v23
	v_cvt_pk_f16_f32 v18, v24, v25
	v_cvt_pk_f16_f32 v19, v26, v27
	global_store_dwordx4 v[94:95], v[16:19], off
	s_nop 0
	v_pk_mul_f32 v[62:63], v[70:71], v[92:93] op_sel_hi:[1,0]
	v_pk_mul_f32 v[64:65], v[74:75], v[92:93] op_sel_hi:[1,0]
	v_pk_mul_f32 v[70:71], v[84:85], v[92:93] op_sel_hi:[1,0]
	v_pk_mul_f32 v[72:73], v[88:89], v[92:93] op_sel_hi:[1,0]
	v_pk_mul_f32 v[74:75], v[86:87], v[92:93] op_sel_hi:[1,0]
	v_pk_fma_f32 v[20:21], v[208:209], v[58:59], v[212:213]
	v_pk_fma_f32 v[24:25], v[204:205], v[60:61], v[216:217]
	v_pk_fma_f32 v[22:23], v[210:211], v[62:63], v[214:215]
	v_pk_fma_f32 v[26:27], v[206:207], v[64:65], v[218:219]
	v_cvt_pk_f16_f32 v16, v20, v21
	v_cvt_pk_f16_f32 v17, v22, v23
	v_cvt_pk_f16_f32 v18, v24, v25
	v_cvt_pk_f16_f32 v19, v26, v27
	global_store_dwordx4 v[94:95], v[16:19], off offset:1024
	s_nop 0
	v_pk_mul_f32 v[58:59], v[76:77], v[92:93] op_sel_hi:[1,0]
	v_pk_mul_f32 v[60:61], v[80:81], v[92:93] op_sel_hi:[1,0]
	v_pk_mul_f32 v[62:63], v[78:79], v[92:93] op_sel_hi:[1,0]
	v_pk_mul_f32 v[64:65], v[82:83], v[92:93] op_sel_hi:[1,0]
	v_pk_mul_f32 v[76:77], v[90:91], v[92:93] op_sel_hi:[1,0]
	v_pk_fma_f32 v[20:21], v[224:225], v[58:59], v[228:229]
	v_pk_fma_f32 v[24:25], v[220:221], v[60:61], v[232:233]
	v_pk_fma_f32 v[22:23], v[226:227], v[62:63], v[230:231]
	v_pk_fma_f32 v[26:27], v[222:223], v[64:65], v[234:235]
	v_cvt_pk_f16_f32 v16, v20, v21
	v_cvt_pk_f16_f32 v17, v22, v23
	v_cvt_pk_f16_f32 v18, v24, v25
	v_cvt_pk_f16_f32 v19, v26, v27
	global_store_dwordx4 v[94:95], v[16:19], off offset:2048
	s_nop 0
	v_mov_b64_e32 v[30:31], v[2:3]
	v_mov_b64_e32 v[26:27], v[6:7]
	v_mov_b64_e32 v[22:23], v[10:11]
	v_mov_b64_e32 v[28:29], v[0:1]
	v_mov_b64_e32 v[24:25], v[4:5]
	v_mov_b64_e32 v[20:21], v[8:9]
	v_pk_fma_f32 v[58:59], v[244:245], v[70:71], v[248:249]
	v_pk_fma_f32 v[62:63], v[240:241], v[72:73], v[252:253]
	v_pk_fma_f32 v[60:61], v[246:247], v[74:75], v[250:251]
	v_pk_fma_f32 v[64:65], v[242:243], v[76:77], v[254:255]
	v_cvt_pk_f16_f32 v16, v58, v59
	v_cvt_pk_f16_f32 v17, v60, v61
	v_cvt_pk_f16_f32 v18, v62, v63
	v_cvt_pk_f16_f32 v19, v64, v65
	global_store_dwordx4 v[94:95], v[16:19], off offset:3072
	s_nop 1
	v_mov_b64_e32 v[18:19], v[14:15]
	v_mov_b64_e32 v[16:17], v[12:13]
	s_andn2_b64 exec, exec, s[14:15]
	s_cbranch_execz .LBB0_2531
